# conv_pass loop hand-written: 4 chunks per trip, conv weights hoisted, loads batched; new blocks placed after s_endpgm
# baseline (speedup 1.0000x reference)
; DI float fexp2(float x) { return __builtin_amdgcn_exp2f(x); }
; DI void diff_pass(const bf16_t* __restrict__ qrow  , const bf16_t* __restrict__ kg, const bf16_t* __restrict__ vg,
;                   int nkt, int q0, float negM2, f32x16 (&O)[4], float& lsum, char* lds) {
;     ...
;                 for (int kb = 0; kb < 2; ++kb)
; #pragma unroll
;                     for (int i = 0; i < 16; ++i) {
;                         float p = fexp2(Sx[kb][i]);
;                         const int key = kt * 64 + 32 * kb + (i & 3) + 8 * (i >> 2) + 4 * h;
;                         if (key > qpos) p = 0.f;
;                         lsum += p; Sx[kb][i] = p;
;                     }
.LBB0_91:
	s_andn2_saveexec_b64 s[30:31], s[30:31]
	s_cbranch_execz .LBB0_86
	v_add_u32_e32 v114, s55, v185
	v_cmp_le_i32_e32 vcc, v114, v184
	v_add_u32_e32 v116, 2, v114
	s_nop 0
	v_cndmask_b32_e32 v2, 0, v2, vcc
	v_cmp_lt_i32_e32 vcc, v114, v184
	v_add_f32_e32 v115, v186, v2
	s_nop 0
	v_cndmask_b32_e32 v4, 0, v4, vcc
	v_cmp_le_i32_e32 vcc, v116, v184
	v_add_u32_e32 v116, 3, v114
	v_add_f32_e32 v115, v4, v115
	v_cndmask_b32_e32 v6, 0, v6, vcc
	v_cmp_le_i32_e32 vcc, v116, v184
	v_add_u32_e32 v116, 8, v114
	v_add_f32_e32 v115, v6, v115
	v_cndmask_b32_e32 v8, 0, v8, vcc
	v_cmp_le_i32_e32 vcc, v116, v184
	v_add_u32_e32 v116, 9, v114
	v_add_f32_e32 v115, v8, v115
	v_cndmask_b32_e32 v10, 0, v10, vcc
	v_cmp_le_i32_e32 vcc, v116, v184
	v_add_u32_e32 v116, 10, v114
	v_add_f32_e32 v115, v10, v115
	v_cndmask_b32_e32 v12, 0, v12, vcc
	v_cmp_le_i32_e32 vcc, v116, v184
	v_add_u32_e32 v116, 11, v114
	v_add_f32_e32 v115, v12, v115
	v_cndmask_b32_e32 v14, 0, v14, vcc
	v_cmp_le_i32_e32 vcc, v116, v184
	v_add_u32_e32 v116, 16, v114
	v_add_f32_e32 v115, v14, v115
	v_cndmask_b32_e32 v96, 0, v96, vcc
	v_cmp_le_i32_e32 vcc, v116, v184
	v_add_u32_e32 v116, 17, v114
	v_add_f32_e32 v115, v96, v115
	v_cndmask_b32_e32 v100, 0, v100, vcc
	v_cmp_le_i32_e32 vcc, v116, v184
	v_add_u32_e32 v116, 18, v114
	v_add_f32_e32 v115, v100, v115
	v_cndmask_b32_e32 v104, 0, v104, vcc
	v_cmp_le_i32_e32 vcc, v116, v184
	v_add_u32_e32 v116, 19, v114
	v_add_f32_e32 v115, v104, v115
	v_cndmask_b32_e32 v98, 0, v98, vcc
	v_cmp_le_i32_e32 vcc, v116, v184
	v_add_u32_e32 v116, 24, v114
	v_add_f32_e32 v115, v98, v115
	v_cndmask_b32_e32 v102, 0, v102, vcc
	v_cmp_le_i32_e32 vcc, v116, v184
	v_add_u32_e32 v116, 25, v114
	v_add_f32_e32 v115, v102, v115
	v_cndmask_b32_e32 v106, 0, v106, vcc
	v_cmp_le_i32_e32 vcc, v116, v184
	v_add_u32_e32 v116, 26, v114
	v_add_f32_e32 v115, v106, v115
	v_cndmask_b32_e32 v108, 0, v108, vcc
	v_cmp_le_i32_e32 vcc, v116, v184
	v_add_u32_e32 v116, 27, v114
	v_add_f32_e32 v115, v108, v115
	v_cndmask_b32_e32 v112, 0, v112, vcc
	v_cmp_le_i32_e32 vcc, v116, v184
	v_add_u32_e32 v116, 32, v114
	v_add_f32_e32 v115, v112, v115
	v_cndmask_b32_e32 v110, 0, v110, vcc
	v_cmp_le_i32_e32 vcc, v116, v184
	v_add_u32_e32 v116, 33, v114
	v_add_f32_e32 v115, v110, v115
	v_cndmask_b32_e32 v3, 0, v3, vcc
	v_cmp_le_i32_e32 vcc, v116, v184
	v_add_u32_e32 v116, 34, v114
	v_add_f32_e32 v115, v3, v115
	v_cndmask_b32_e32 v5, 0, v5, vcc
	v_cmp_le_i32_e32 vcc, v116, v184
	v_add_u32_e32 v116, 35, v114
	v_add_f32_e32 v115, v5, v115
	v_cndmask_b32_e32 v7, 0, v7, vcc
	v_cmp_le_i32_e32 vcc, v116, v184
	v_add_u32_e32 v116, 40, v114
	v_add_f32_e32 v115, v7, v115
	v_cndmask_b32_e32 v9, 0, v9, vcc
	v_cmp_le_i32_e32 vcc, v116, v184
	v_add_u32_e32 v116, 41, v114
	v_add_f32_e32 v115, v9, v115
	v_cndmask_b32_e32 v11, 0, v11, vcc
	v_cmp_le_i32_e32 vcc, v116, v184
	v_add_u32_e32 v116, 42, v114
	v_add_f32_e32 v115, v11, v115
	v_cndmask_b32_e32 v13, 0, v13, vcc
	v_cmp_le_i32_e32 vcc, v116, v184
	v_add_u32_e32 v116, 43, v114
	v_add_f32_e32 v115, v13, v115
	v_cndmask_b32_e32 v15, 0, v15, vcc
	v_cmp_le_i32_e32 vcc, v116, v184
	v_add_u32_e32 v116, 48, v114
	v_add_f32_e32 v115, v15, v115
	v_cndmask_b32_e32 v97, 0, v97, vcc
	v_cmp_le_i32_e32 vcc, v116, v184
	v_add_u32_e32 v116, 49, v114
	v_add_f32_e32 v115, v97, v115
	v_cndmask_b32_e32 v101, 0, v101, vcc
	v_cmp_le_i32_e32 vcc, v116, v184
	v_add_u32_e32 v116, 50, v114
	v_add_f32_e32 v115, v101, v115
	v_cndmask_b32_e32 v105, 0, v105, vcc
	v_cmp_le_i32_e32 vcc, v116, v184
	v_add_u32_e32 v116, 51, v114
	v_add_f32_e32 v115, v105, v115
	v_cndmask_b32_e32 v99, 0, v99, vcc
	v_cmp_le_i32_e32 vcc, v116, v184
	v_add_u32_e32 v116, 56, v114
	v_add_f32_e32 v115, v99, v115
	v_cndmask_b32_e32 v103, 0, v103, vcc
	v_cmp_le_i32_e32 vcc, v116, v184
	v_add_u32_e32 v116, 57, v114
	v_add_f32_e32 v115, v103, v115
	v_cndmask_b32_e32 v107, 0, v107, vcc
	v_cmp_le_i32_e32 vcc, v116, v184
	v_add_u32_e32 v116, 58, v114
	v_add_f32_e32 v115, v107, v115
	v_cndmask_b32_e32 v109, 0, v109, vcc
	v_cmp_le_i32_e32 vcc, v116, v184
	v_add_u32_e32 v114, 59, v114
	v_add_f32_e32 v115, v109, v115
	v_cndmask_b32_e32 v113, 0, v113, vcc
	v_cmp_le_i32_e32 vcc, v114, v184
	v_add_f32_e32 v115, v113, v115
	s_nop 0
	v_cndmask_b32_e32 v111, 0, v111, vcc
	v_add_f32_e32 v186, v111, v115
	s_branch .LBB0_86
; #define MFMA(a, b, c) __builtin_amdgcn_mfma_f32_32x32x16_bf16((a), (b), (c), 0, 0, 0)
; DI float fexp2(float x) { return __builtin_amdgcn_exp2f(x); }
; DI void diff_pass(const bf16_t* __restrict__ qrow  , const bf16_t* __restrict__ kg, const bf16_t* __restrict__ vg,
;                   int nkt, int q0, float negM2, f32x16 (&O)[4], float& lsum, char* lds) {
;     ...
;         if (kt * 64 <= q0 + 31) {
;             f32x16 Sx[2];
;             {
;                 bf16x8 kf[2][4];
; #pragma unroll
;                 for (int kb = 0; kb < 2; ++kb)
; #pragma unroll
;                     for (int ks = 0; ks < 4; ++ks) kf[kb][ks] = *(const bf16x8*)(st + (32 * kb + l31) * 128 + (((2 * ks + h) ^ f) << 4));
;                 __builtin_amdgcn_sched_barrier(0);
; #pragma unroll
;                 for (int ks = 0; ks < 4; ++ks)
; #pragma unroll
;                     for (int kb = 0; kb < 2; ++kb) Sx[kb] = ks == 0 ? MFMA(kf[kb][0], qf[0], minit) : MFMA(kf[kb][ks], qf[ks], Sx[kb]);
;             }
;             if (kt * 64 + 63 > q0) {
; #pragma unroll
;                 for (int kb = 0; kb < 2; ++kb)
; #pragma unroll
;                     for (int i = 0; i < 16; ++i) {
;                         float p = fexp2(Sx[kb][i]);
;                         const int key = kt * 64 + 32 * kb + (i & 3) + 8 * (i >> 2) + 4 * h;
;                         if (key > qpos) p = 0.f;
;                         lsum += p; Sx[kb][i] = p;
;                     }
;             } else {
;                 float l0 = 0.f, l1 = 0.f;
; #pragma unroll
;                 for (int i = 0; i < 16; ++i) { const float p0 = fexp2(Sx[0][i]), p1 = fexp2(Sx[1][i]); l0 += p0; l1 += p1; Sx[0][i] = p0; Sx[1][i] = p1; }
;                 lsum += l0 + l1;
;             }
.LBB0_93:
	v_cmp_le_i32_e32 vcc, s35, v171
	s_and_saveexec_b64 s[28:29], vcc
	s_cbranch_execz .LBB0_99
	v_add_u32_e32 v160, v188, v189
	v_add_u32_e32 v159, v188, v190
	v_add_u32_e32 v158, v188, v191
	v_add_u32_e32 v0, v188, v192
	ds_read_b128 v[2:5], v160 offset:24576
	ds_read_b128 v[6:9], v160 offset:28672
	ds_read_b128 v[10:13], v159 offset:24576
	ds_read_b128 v[188:191], v159 offset:28672
	ds_read_b128 v[192:195], v158 offset:24576
	ds_read_b128 v[196:199], v158 offset:28672
	ds_read_b128 v[200:203], v0 offset:24576
	ds_read_b128 v[204:207], v0 offset:28672
	s_waitcnt lgkmcnt(7)
	v_mfma_f32_32x32x16_bf16 v[96:111], v[2:5], v[140:143], v[16:31]
	s_or_b32 s30, s35, 63
	v_cmp_le_i32_e32 vcc, s30, v148
	s_waitcnt lgkmcnt(6)
	v_mfma_f32_32x32x16_bf16 v[112:127], v[6:9], v[140:143], v[16:31]
	s_waitcnt lgkmcnt(5)
	v_mfma_f32_32x32x16_bf16 v[96:111], v[10:13], v[136:139], v[96:111]
	s_waitcnt lgkmcnt(4)
	v_mfma_f32_32x32x16_bf16 v[112:127], v[188:191], v[136:139], v[112:127]
	s_waitcnt lgkmcnt(3)
	v_mfma_f32_32x32x16_bf16 v[96:111], v[192:195], v[132:135], v[96:111]
	s_waitcnt lgkmcnt(2)
	v_mfma_f32_32x32x16_bf16 v[112:127], v[196:199], v[132:135], v[112:127]
	s_waitcnt lgkmcnt(1)
	v_mfma_f32_32x32x16_bf16 v[96:111], v[200:203], v[128:131], v[96:111]
	s_waitcnt lgkmcnt(0)
	v_mfma_f32_32x32x16_bf16 v[112:127], v[204:207], v[128:131], v[112:127]
	s_nop 9
	v_exp_f32_e32 v2, v96
	v_exp_f32_e32 v4, v97
	v_exp_f32_e32 v6, v98
	v_exp_f32_e32 v8, v99
	v_exp_f32_e32 v10, v100
	v_exp_f32_e32 v12, v101
	v_exp_f32_e32 v14, v102
	v_exp_f32_e32 v3, v112
	v_exp_f32_e32 v5, v113
	v_exp_f32_e32 v7, v114
	v_exp_f32_e32 v9, v115
	v_exp_f32_e32 v11, v116
	v_exp_f32_e32 v13, v117
	v_exp_f32_e32 v15, v118
	v_exp_f32_e32 v96, v103
	v_exp_f32_e32 v97, v119
	v_exp_f32_e32 v100, v104
	v_exp_f32_e32 v101, v120
	v_exp_f32_e32 v104, v105
	v_exp_f32_e32 v105, v121
	v_exp_f32_e32 v98, v106
	v_exp_f32_e32 v99, v122
	v_exp_f32_e32 v102, v107
	v_exp_f32_e32 v103, v123
	v_exp_f32_e32 v106, v108
	v_exp_f32_e32 v107, v124
	v_exp_f32_e32 v108, v109
	v_exp_f32_e32 v109, v125
	v_exp_f32_e32 v112, v110
	v_exp_f32_e32 v113, v126
	v_exp_f32_e32 v110, v111
	v_exp_f32_e32 v111, v127
	s_and_saveexec_b64 s[30:31], vcc
	s_xor_b64 s[30:31], exec, s[30:31]
	s_cbranch_execz .LBB0_96
	v_pk_add_f32 v[114:115], v[2:3], 0 op_sel_hi:[1,0]
	s_nop 0
	v_pk_add_f32 v[114:115], v[4:5], v[114:115]
	s_nop 0
	v_pk_add_f32 v[114:115], v[6:7], v[114:115]
	s_nop 0
	v_pk_add_f32 v[114:115], v[8:9], v[114:115]
	s_nop 0
	v_pk_add_f32 v[114:115], v[10:11], v[114:115]
	s_nop 0
	v_pk_add_f32 v[114:115], v[12:13], v[114:115]
	s_nop 0
	v_pk_add_f32 v[114:115], v[14:15], v[114:115]
	s_nop 0
	v_pk_add_f32 v[114:115], v[96:97], v[114:115]
	s_nop 0
	v_pk_add_f32 v[114:115], v[100:101], v[114:115]
	s_nop 0
	v_pk_add_f32 v[114:115], v[104:105], v[114:115]
	s_nop 0
	v_pk_add_f32 v[114:115], v[98:99], v[114:115]
	s_nop 0
	v_pk_add_f32 v[114:115], v[102:103], v[114:115]
	s_nop 0
	v_pk_add_f32 v[114:115], v[106:107], v[114:115]
	s_nop 0
	v_pk_add_f32 v[114:115], v[108:109], v[114:115]
	s_nop 0
	v_pk_add_f32 v[114:115], v[112:113], v[114:115]
	s_nop 0
	v_pk_add_f32 v[114:115], v[110:111], v[114:115]
	s_nop 0
	v_add_f32_e32 v114, v114, v115
	v_add_f32_e32 v114, v186, v114

; DI void diff_pass(const bf16_t* __restrict__ qrow  , const bf16_t* __restrict__ kg, const bf16_t* __restrict__ vg,
;                   int nkt, int q0, float negM2, f32x16 (&O)[4], float& lsum, char* lds) {
;     ...
;             f32x16 Sx[2];
;             {
;                 bf16x8 kf[2][4];
; #pragma unroll
;                 for (int kb = 0; kb < 2; ++kb)
; #pragma unroll
;                     for (int ks = 0; ks < 4; ++ks) kf[kb][ks] = *(const bf16x8*)(st + (32 * kb + l31) * 128 + (((2 * ks + h) ^ f) << 4));
;                 __builtin_amdgcn_sched_barrier(0);
; #pragma unroll
;                 for (int ks = 0; ks < 4; ++ks)
; #pragma unroll
;                     for (int kb = 0; kb < 2; ++kb) Sx[kb] = ks == 0 ? MFMA(kf[kb][0], qf[0], minit) : MFMA(kf[kb][ks], qf[ks], Sx[kb]);
;             }
;             if (kt * 64 + 63 > q0) {
; #pragma unroll
;                 for (int kb = 0; kb < 2; ++kb)
; #pragma unroll
;                     for (int i = 0; i < 16; ++i) {
;                         float p = fexp2(Sx[kb][i]);
;                         const int key = kt * 64 + 32 * kb + (i & 3) + 8 * (i >> 2) + 4 * h;
;                         if (key > qpos) p = 0.f;
;                         lsum += p; Sx[kb][i] = p;
;                     }
;             } else {
;                 float l0 = 0.f, l1 = 0.f;
; #pragma unroll
;                 for (int i = 0; i < 16; ++i) { const float p0 = fexp2(Sx[0][i]), p1 = fexp2(Sx[1][i]); l0 += p0; l1 += p1; Sx[0][i] = p0; Sx[1][i] = p1; }
;                 lsum += l0 + l1;
;             }
;             bf16x8 pf[4];
;             pf[0] = pack8(Sx[0], 0); pf[1] = pack8(Sx[0], 1); pf[2] = pack8(Sx[1], 0); pf[3] = pack8(Sx[1], 1);
;             {
;                 bf16x8 vf[2][4];
; #pragma unroll
;                 for (int db = 0; db < 4; ++db) vf[0][db] = *(const bf16x8*)(st + 8192 + (32 * db + l31) * 128 + ((h ^ f) << 4));
; #pragma unroll
;                 for (int s = 0; s < 4; ++s) {
;                     if (s < 3) {
; #pragma unroll
;                         for (int db = 0; db < 4; ++db) vf[(s + 1) & 1][db] = *(const bf16x8*)(st + 8192 + (32 * db + l31) * 128 + (((2 * (s + 1) + h) ^ f) << 4));
;                     }
; #pragma unroll
;                     for (int db = 0; db < 4; ++db) O[db] = MFMA(vf[s & 1][db], pf[s], O[db]);
;                     __builtin_amdgcn_sched_barrier(0);
;                 }
;             }
.LBB0_512:
	s_endpgm
.Ldf_fast:
	ds_read_b128 v[2:5], v195
	ds_read_b128 v[10:13], v194
	ds_read_b128 v[200:203], v193
	ds_read_b128 v[208:211], v0
	ds_read_b128 v[6:9], v195 offset:4096
	ds_read_b128 v[196:199], v194 offset:4096
	ds_read_b128 v[204:207], v193 offset:4096
	ds_read_b128 v[212:215], v0 offset:4096
	v_mov_b32_e32 v14, 0
	v_mov_b32_e32 v15, 0
	s_waitcnt lgkmcnt(7)
	v_mfma_f32_32x32x16_bf16 v[96:111], v[2:5], v[140:143], v[16:31]
	s_waitcnt lgkmcnt(6)
	v_mfma_f32_32x32x16_bf16 v[96:111], v[10:13], v[136:139], v[96:111]
	s_waitcnt lgkmcnt(5)
	v_mfma_f32_32x32x16_bf16 v[96:111], v[200:203], v[132:135], v[96:111]
	s_waitcnt lgkmcnt(4)
	v_mfma_f32_32x32x16_bf16 v[96:111], v[208:211], v[128:131], v[96:111]
	s_waitcnt lgkmcnt(3)
	v_mfma_f32_32x32x16_bf16 v[112:127], v[6:9], v[140:143], v[16:31]
	ds_read_b128 v[2:5], v195 offset:8192
	ds_read_b128 v[10:13], v195 offset:12288
	s_waitcnt lgkmcnt(4)
	v_mfma_f32_32x32x16_bf16 v[112:127], v[196:199], v[136:139], v[112:127]
	ds_read_b128 v[200:203], v195 offset:16384
	ds_read_b128 v[208:211], v195 offset:20480
	s_nop 3
	v_exp_f32_e32 v96, v96
	v_exp_f32_e32 v97, v97
	v_add_f32_e32 v14, v14, v96
	v_add_f32_e32 v14, v14, v97
	s_waitcnt lgkmcnt(5)
	v_mfma_f32_32x32x16_bf16 v[112:127], v[204:207], v[132:135], v[112:127]
	v_exp_f32_e32 v98, v98
	v_exp_f32_e32 v99, v99
	v_add_f32_e32 v14, v14, v98
	v_add_f32_e32 v14, v14, v99
	s_waitcnt lgkmcnt(4)
	v_mfma_f32_32x32x16_bf16 v[112:127], v[212:215], v[128:131], v[112:127]
	v_exp_f32_e32 v100, v100
	v_exp_f32_e32 v101, v101
	v_add_f32_e32 v14, v14, v100
	v_add_f32_e32 v14, v14, v101
	v_exp_f32_e32 v102, v102
	v_exp_f32_e32 v103, v103
	v_add_f32_e32 v14, v14, v102
	v_add_f32_e32 v14, v14, v103
	v_cvt_pk_bf16_f32 v96, v96, v97
	v_cvt_pk_bf16_f32 v97, v98, v99
	v_cvt_pk_bf16_f32 v98, v100, v101
	v_cvt_pk_bf16_f32 v99, v102, v103
	s_waitcnt lgkmcnt(3)
	s_nop 0
	v_mfma_f32_32x32x16_bf16 v[80:95], v[2:5], v[96:99], v[80:95]
	ds_read_b128 v[6:9], v194 offset:8192
	ds_read_b128 v[196:199], v194 offset:12288
	ds_read_b128 v[204:207], v194 offset:16384
	ds_read_b128 v[212:215], v194 offset:20480
	v_exp_f32_e32 v104, v104
	v_exp_f32_e32 v105, v105
	v_add_f32_e32 v14, v14, v104
	v_add_f32_e32 v14, v14, v105
	s_waitcnt lgkmcnt(6)
	v_mfma_f32_32x32x16_bf16 v[64:79], v[10:13], v[96:99], v[64:79]
	ds_read_b128 v[2:5], v193 offset:8192
	v_exp_f32_e32 v106, v106
	v_exp_f32_e32 v107, v107
	v_add_f32_e32 v14, v14, v106
	v_add_f32_e32 v14, v14, v107
	s_waitcnt lgkmcnt(6)
	v_mfma_f32_32x32x16_bf16 v[48:63], v[200:203], v[96:99], v[48:63]
	ds_read_b128 v[10:13], v193 offset:12288
	v_exp_f32_e32 v108, v108
	v_exp_f32_e32 v109, v109
	v_add_f32_e32 v14, v14, v108
	v_add_f32_e32 v14, v14, v109
	s_waitcnt lgkmcnt(6)
	v_mfma_f32_32x32x16_bf16 v[32:47], v[208:211], v[96:99], v[32:47]
	ds_read_b128 v[200:203], v193 offset:16384
	v_exp_f32_e32 v110, v110
	v_exp_f32_e32 v111, v111
	v_add_f32_e32 v14, v14, v110
	v_add_f32_e32 v14, v14, v111
	v_cvt_pk_bf16_f32 v104, v104, v105
	v_cvt_pk_bf16_f32 v105, v106, v107
	v_cvt_pk_bf16_f32 v106, v108, v109
	v_cvt_pk_bf16_f32 v107, v110, v111
	s_waitcnt lgkmcnt(6)
	s_nop 0
	v_mfma_f32_32x32x16_bf16 v[80:95], v[6:9], v[104:107], v[80:95]
	ds_read_b128 v[208:211], v193 offset:20480
	v_exp_f32_e32 v112, v112
	v_exp_f32_e32 v113, v113
	v_add_f32_e32 v15, v15, v112
	v_add_f32_e32 v15, v15, v113
	s_waitcnt lgkmcnt(6)
	v_mfma_f32_32x32x16_bf16 v[64:79], v[196:199], v[104:107], v[64:79]
	ds_read_b128 v[6:9], v0 offset:8192
	v_exp_f32_e32 v114, v114
	v_exp_f32_e32 v115, v115
	v_add_f32_e32 v15, v15, v114
	v_add_f32_e32 v15, v15, v115
	s_waitcnt lgkmcnt(6)
	v_mfma_f32_32x32x16_bf16 v[48:63], v[204:207], v[104:107], v[48:63]
	ds_read_b128 v[196:199], v0 offset:12288
	v_exp_f32_e32 v116, v116
	v_exp_f32_e32 v117, v117
	v_add_f32_e32 v15, v15, v116
	v_add_f32_e32 v15, v15, v117
	s_waitcnt lgkmcnt(6)
	v_mfma_f32_32x32x16_bf16 v[32:47], v[212:215], v[104:107], v[32:47]
	ds_read_b128 v[204:207], v0 offset:16384
	v_exp_f32_e32 v118, v118
	v_exp_f32_e32 v119, v119
	v_add_f32_e32 v15, v15, v118
	v_add_f32_e32 v15, v15, v119
	v_cvt_pk_bf16_f32 v112, v112, v113
	v_cvt_pk_bf16_f32 v113, v114, v115
	v_cvt_pk_bf16_f32 v114, v116, v117
	v_cvt_pk_bf16_f32 v115, v118, v119
	s_waitcnt lgkmcnt(6)
	s_nop 0
	v_mfma_f32_32x32x16_bf16 v[80:95], v[2:5], v[112:115], v[80:95]
	ds_read_b128 v[212:215], v0 offset:20480
	v_exp_f32_e32 v120, v120
	v_exp_f32_e32 v121, v121
	v_add_f32_e32 v15, v15, v120
	v_add_f32_e32 v15, v15, v121
	s_waitcnt lgkmcnt(6)
	v_mfma_f32_32x32x16_bf16 v[64:79], v[10:13], v[112:115], v[64:79]
	v_exp_f32_e32 v122, v122
	v_exp_f32_e32 v123, v123
	v_add_f32_e32 v15, v15, v122
	v_add_f32_e32 v15, v15, v123
	s_waitcnt lgkmcnt(5)
	v_mfma_f32_32x32x16_bf16 v[48:63], v[200:203], v[112:115], v[48:63]
	v_exp_f32_e32 v124, v124
	v_exp_f32_e32 v125, v125
	v_add_f32_e32 v15, v15, v124
	v_add_f32_e32 v15, v15, v125
	s_waitcnt lgkmcnt(4)
	v_mfma_f32_32x32x16_bf16 v[32:47], v[208:211], v[112:115], v[32:47]
	v_exp_f32_e32 v126, v126
	v_exp_f32_e32 v127, v127
	v_add_f32_e32 v15, v15, v126
	v_add_f32_e32 v15, v15, v127
	v_cvt_pk_bf16_f32 v120, v120, v121
	v_cvt_pk_bf16_f32 v121, v122, v123
	v_cvt_pk_bf16_f32 v122, v124, v125
	v_cvt_pk_bf16_f32 v123, v126, v127
	v_add_f32_e32 v14, v14, v15
	s_waitcnt lgkmcnt(3)
	v_mfma_f32_32x32x16_bf16 v[80:95], v[6:9], v[120:123], v[80:95]
	v_add_f32_e32 v186, v186, v14
	s_waitcnt lgkmcnt(2)
	v_mfma_f32_32x32x16_bf16 v[64:79], v[196:199], v[120:123], v[64:79]
	s_waitcnt lgkmcnt(1)
	v_mfma_f32_32x32x16_bf16 v[48:63], v[204:207], v[120:123], v[48:63]
	s_waitcnt lgkmcnt(0)
	v_mfma_f32_32x32x16_bf16 v[32:47], v[212:215], v[120:123], v[32:47]
	s_branch .LBB0_87
; DI int tid() { int t = __builtin_amdgcn_workitem_id_x(); asm volatile("" : "+v"(t)); return t; }
; DI unsigned pk2(float a, float b) { f32x2 v = {a, b}; return __builtin_bit_cast(unsigned, __builtin_convertvector(v, bf2_t)); }
; DI float bf_lo(unsigned u) { return __uint_as_float(u << 16); }
; DI float bf_hi(unsigned u) { return __uint_as_float(u & 0xffff0000u); }
; DI bf16_t* slotp(const Params& P, int s) { return (bf16_t*)(P.ws + OFF_PROJ + (size_t)s * PROJ_SLOT); }
; DI void conv_pass(const Params& P, int layer) {
;     const bf16_t* cu = slotp(P, SL_CU); bf16_t* bz = slotp(P, SL_BZ);
;     const float* cw = P.conv_w + layer * 3 * 512;
;     for (int idx = blockIdx.x * 512 + tid(); idx < kT * 64; idx += gridDim.x * 512) {
;         const int tok = idx >> 6, c8 = (idx & 63) * 8, pos = tok & (kS - 1);
;         const u32x4 z4 = {0u, 0u, 0u, 0u};
;         const u32x4 c2 = *(const u32x4*)(cu + (size_t)tok * 512 + c8);
;         const u32x4 c1 = pos >= 1 ? *(const u32x4*)(cu + (size_t)(tok - 1) * 512 + c8) : z4;
;         const u32x4 c0 = pos >= 2 ? *(const u32x4*)(cu + (size_t)(tok - 2) * 512 + c8) : z4;
;         const u32x4 bv = *(const u32x4*)(bz + (size_t)tok * 512 + c8);
;         u32x4 o;
; #pragma unroll
;         for (int j = 0; j < 4; ++j) {
;             const int ch = c8 + 2 * j;
;             const float r0 = bf_lo(bv[j]) * (cw[ch] * bf_lo(c0[j]) + cw[512 + ch] * bf_lo(c1[j]) + cw[1024 + ch] * bf_lo(c2[j]));
;             const float r1 = bf_hi(bv[j]) * (cw[ch + 1] * bf_hi(c0[j]) + cw[512 + ch + 1] * bf_hi(c1[j]) + cw[1024 + ch + 1] * bf_hi(c2[j]));
;             o[j] = pk2(r0, r1);
;         }
;         *(u32x4*)(bz + (size_t)tok * 512 + c8) = o;
;     }
; }
.Lconv_fast:
	s_mul_i32 s12, s2, 3
	v_add_u32_e32 v5, s12, v24
	s_mov_b32 s13, 0x200000
	v_cmp_gt_i32_e32 vcc, s13, v5
	s_cbranch_vccz .LBB0_73
	v_readlane_b32 s12, v253, 44
	v_readlane_b32 s13, v253, 45
	v_readlane_b32 s14, v253, 38
	v_readlane_b32 s15, v253, 39
	v_and_b32_e32 v2, 0x1f8, v25
	v_lshlrev_b32_e32 v3, 2, v2
	v_lshlrev_b32_e32 v2, 1, v2
	v_add_u32_e32 v4, 0x1000, v3
	global_load_dwordx4 v[26:29], v3, s[8:9]
	global_load_dwordx4 v[30:33], v3, s[8:9] offset:16
	global_load_dwordx4 v[34:37], v3, s[8:9] offset:2048
	global_load_dwordx4 v[38:41], v3, s[8:9] offset:2064
	global_load_dwordx4 v[42:45], v4, s[8:9]
	global_load_dwordx4 v[46:49], v4, s[8:9] offset:16
.Lconv_loop:
	v_mov_b32_e32 v5, v24
	v_ashrrev_i32_e32 v6, 6, v5
	v_lshl_add_u32 v74, v6, 10, v2
	v_and_b32_e32 v75, 0x1fff, v6
	v_add_u32_e32 v5, s2, v5
	global_load_dwordx4 v[50:53], v74, s[12:13]
	global_load_dwordx4 v[54:57], v74, s[12:13] offset:-1024
	global_load_dwordx4 v[58:61], v74, s[12:13] offset:-2048
	global_load_dwordx4 v[62:65], v74, s[14:15]
	v_ashrrev_i32_e32 v6, 6, v5
	v_lshl_add_u32 v100, v6, 10, v2
	v_and_b32_e32 v101, 0x1fff, v6
	v_add_u32_e32 v5, s2, v5
	global_load_dwordx4 v[76:79], v100, s[12:13]
	global_load_dwordx4 v[80:83], v100, s[12:13] offset:-1024
	global_load_dwordx4 v[84:87], v100, s[12:13] offset:-2048
	global_load_dwordx4 v[88:91], v100, s[14:15]
	v_ashrrev_i32_e32 v6, 6, v5
	v_lshl_add_u32 v126, v6, 10, v2
	v_and_b32_e32 v127, 0x1fff, v6
	v_add_u32_e32 v5, s2, v5
	global_load_dwordx4 v[102:105], v126, s[12:13]
	global_load_dwordx4 v[106:109], v126, s[12:13] offset:-1024
	global_load_dwordx4 v[110:113], v126, s[12:13] offset:-2048
	global_load_dwordx4 v[114:117], v126, s[14:15]
	v_ashrrev_i32_e32 v6, 6, v5
	v_lshl_add_u32 v152, v6, 10, v2
	v_and_b32_e32 v153, 0x1fff, v6
	global_load_dwordx4 v[128:131], v152, s[12:13]
	global_load_dwordx4 v[132:135], v152, s[12:13] offset:-1024
	global_load_dwordx4 v[136:139], v152, s[12:13] offset:-2048
	global_load_dwordx4 v[140:143], v152, s[14:15]
	s_waitcnt vmcnt(12)
	v_cmp_ne_u32_e32 vcc, 0, v75
	v_cmp_lt_u32_e64 s[0:1], 1, v75
	v_lshlrev_b32_e32 v70, 16, v50
	v_and_b32_e32 v71, 0xffff0000, v50
	v_lshlrev_b32_e32 v72, 16, v62
	v_and_b32_e32 v73, 0xffff0000, v62
	v_cndmask_b32_e32 v54, 0, v54, vcc
	v_cndmask_b32_e64 v58, 0, v58, s[0:1]
	v_lshlrev_b32_e32 v68, 16, v54
	v_and_b32_e32 v69, 0xffff0000, v54
	v_lshlrev_b32_e32 v66, 16, v58
	v_and_b32_e32 v67, 0xffff0000, v58
	v_pk_mul_f32 v[68:69], v[34:35], v[68:69]
	s_nop 0
	v_pk_fma_f32 v[68:69], v[26:27], v[66:67], v[68:69]
	s_nop 0
	v_pk_fma_f32 v[68:69], v[42:43], v[70:71], v[68:69]
	s_nop 0
	v_pk_mul_f32 v[68:69], v[68:69], v[72:73]
	s_nop 0
	v_cvt_pk_bf16_f32 v50, v68, v69
	v_lshlrev_b32_e32 v70, 16, v51
	v_and_b32_e32 v71, 0xffff0000, v51
	v_lshlrev_b32_e32 v72, 16, v63
	v_and_b32_e32 v73, 0xffff0000, v63
	v_cndmask_b32_e32 v55, 0, v55, vcc
	v_cndmask_b32_e64 v59, 0, v59, s[0:1]
	v_lshlrev_b32_e32 v68, 16, v55
	v_and_b32_e32 v69, 0xffff0000, v55
	v_lshlrev_b32_e32 v66, 16, v59
	v_and_b32_e32 v67, 0xffff0000, v59
	v_pk_mul_f32 v[68:69], v[36:37], v[68:69]
	s_nop 0
	v_pk_fma_f32 v[68:69], v[28:29], v[66:67], v[68:69]
	s_nop 0
	v_pk_fma_f32 v[68:69], v[44:45], v[70:71], v[68:69]
	s_nop 0
	v_pk_mul_f32 v[68:69], v[68:69], v[72:73]
	s_nop 0
	v_cvt_pk_bf16_f32 v51, v68, v69
	v_lshlrev_b32_e32 v70, 16, v52
	v_and_b32_e32 v71, 0xffff0000, v52
	v_lshlrev_b32_e32 v72, 16, v64
	v_and_b32_e32 v73, 0xffff0000, v64
	v_cndmask_b32_e32 v56, 0, v56, vcc
	v_cndmask_b32_e64 v60, 0, v60, s[0:1]
	v_lshlrev_b32_e32 v68, 16, v56
	v_and_b32_e32 v69, 0xffff0000, v56
	v_lshlrev_b32_e32 v66, 16, v60
	v_and_b32_e32 v67, 0xffff0000, v60
	v_pk_mul_f32 v[68:69], v[38:39], v[68:69]
	s_nop 0
	v_pk_fma_f32 v[68:69], v[30:31], v[66:67], v[68:69]
	s_nop 0
	v_pk_fma_f32 v[68:69], v[46:47], v[70:71], v[68:69]
	s_nop 0
	v_pk_mul_f32 v[68:69], v[68:69], v[72:73]
	s_nop 0
	v_cvt_pk_bf16_f32 v52, v68, v69
	v_lshlrev_b32_e32 v70, 16, v53
	v_and_b32_e32 v71, 0xffff0000, v53
	v_lshlrev_b32_e32 v72, 16, v65
	v_and_b32_e32 v73, 0xffff0000, v65
	v_cndmask_b32_e32 v57, 0, v57, vcc
	v_cndmask_b32_e64 v61, 0, v61, s[0:1]
	v_lshlrev_b32_e32 v68, 16, v57
	v_and_b32_e32 v69, 0xffff0000, v57
	v_lshlrev_b32_e32 v66, 16, v61
	v_and_b32_e32 v67, 0xffff0000, v61
	v_pk_mul_f32 v[68:69], v[40:41], v[68:69]
	s_nop 0
	v_pk_fma_f32 v[68:69], v[32:33], v[66:67], v[68:69]
	s_nop 0
	v_pk_fma_f32 v[68:69], v[48:49], v[70:71], v[68:69]
	s_nop 0
	v_pk_mul_f32 v[68:69], v[68:69], v[72:73]
	s_nop 0
	v_cvt_pk_bf16_f32 v53, v68, v69
	global_store_dwordx4 v74, v[50:53], s[14:15]
	s_waitcnt vmcnt(9)
; DI unsigned pk2(float a, float b) { f32x2 v = {a, b}; return __builtin_bit_cast(unsigned, __builtin_convertvector(v, bf2_t)); }
; DI float bf_lo(unsigned u) { return __uint_as_float(u << 16); }
; DI float bf_hi(unsigned u) { return __uint_as_float(u & 0xffff0000u); }
; DI void conv_pass(const Params& P, int layer) {
;     ...
; #pragma unroll
;         for (int j = 0; j < 4; ++j) {
;             const int ch = c8 + 2 * j;
;             const float r0 = bf_lo(bv[j]) * (cw[ch] * bf_lo(c0[j]) + cw[512 + ch] * bf_lo(c1[j]) + cw[1024 + ch] * bf_lo(c2[j]));
;             const float r1 = bf_hi(bv[j]) * (cw[ch + 1] * bf_hi(c0[j]) + cw[512 + ch + 1] * bf_hi(c1[j]) + cw[1024 + ch + 1] * bf_hi(c2[j]));
;             o[j] = pk2(r0, r1);
;         }
;         *(u32x4*)(bz + (size_t)tok * 512 + c8) = o;
	v_cmp_ne_u32_e32 vcc, 0, v101
	v_cmp_lt_u32_e64 s[0:1], 1, v101
	v_lshlrev_b32_e32 v96, 16, v76
	v_and_b32_e32 v97, 0xffff0000, v76
	v_lshlrev_b32_e32 v98, 16, v88
	v_and_b32_e32 v99, 0xffff0000, v88
	v_cndmask_b32_e32 v80, 0, v80, vcc
	v_cndmask_b32_e64 v84, 0, v84, s[0:1]
	v_lshlrev_b32_e32 v94, 16, v80
	v_and_b32_e32 v95, 0xffff0000, v80
	v_lshlrev_b32_e32 v92, 16, v84
	v_and_b32_e32 v93, 0xffff0000, v84
	v_pk_mul_f32 v[94:95], v[34:35], v[94:95]
	s_nop 0
	v_pk_fma_f32 v[94:95], v[26:27], v[92:93], v[94:95]
	s_nop 0
	v_pk_fma_f32 v[94:95], v[42:43], v[96:97], v[94:95]
	s_nop 0
	v_pk_mul_f32 v[94:95], v[94:95], v[98:99]
	s_nop 0
	v_cvt_pk_bf16_f32 v76, v94, v95
	v_lshlrev_b32_e32 v96, 16, v77
	v_and_b32_e32 v97, 0xffff0000, v77
	v_lshlrev_b32_e32 v98, 16, v89
	v_and_b32_e32 v99, 0xffff0000, v89
	v_cndmask_b32_e32 v81, 0, v81, vcc
	v_cndmask_b32_e64 v85, 0, v85, s[0:1]
	v_lshlrev_b32_e32 v94, 16, v81
	v_and_b32_e32 v95, 0xffff0000, v81
	v_lshlrev_b32_e32 v92, 16, v85
	v_and_b32_e32 v93, 0xffff0000, v85
	v_pk_mul_f32 v[94:95], v[36:37], v[94:95]
	s_nop 0
	v_pk_fma_f32 v[94:95], v[28:29], v[92:93], v[94:95]
	s_nop 0
	v_pk_fma_f32 v[94:95], v[44:45], v[96:97], v[94:95]
	s_nop 0
	v_pk_mul_f32 v[94:95], v[94:95], v[98:99]
	s_nop 0
	v_cvt_pk_bf16_f32 v77, v94, v95
	v_lshlrev_b32_e32 v96, 16, v78
	v_and_b32_e32 v97, 0xffff0000, v78
	v_lshlrev_b32_e32 v98, 16, v90
	v_and_b32_e32 v99, 0xffff0000, v90
	v_cndmask_b32_e32 v82, 0, v82, vcc
	v_cndmask_b32_e64 v86, 0, v86, s[0:1]
	v_lshlrev_b32_e32 v94, 16, v82
	v_and_b32_e32 v95, 0xffff0000, v82
	v_lshlrev_b32_e32 v92, 16, v86
	v_and_b32_e32 v93, 0xffff0000, v86
	v_pk_mul_f32 v[94:95], v[38:39], v[94:95]
	s_nop 0
	v_pk_fma_f32 v[94:95], v[30:31], v[92:93], v[94:95]
	s_nop 0
	v_pk_fma_f32 v[94:95], v[46:47], v[96:97], v[94:95]
	s_nop 0
	v_pk_mul_f32 v[94:95], v[94:95], v[98:99]
	s_nop 0
	v_cvt_pk_bf16_f32 v78, v94, v95
	v_lshlrev_b32_e32 v96, 16, v79
	v_and_b32_e32 v97, 0xffff0000, v79
	v_lshlrev_b32_e32 v98, 16, v91
	v_and_b32_e32 v99, 0xffff0000, v91
	v_cndmask_b32_e32 v83, 0, v83, vcc
	v_cndmask_b32_e64 v87, 0, v87, s[0:1]
	v_lshlrev_b32_e32 v94, 16, v83
	v_and_b32_e32 v95, 0xffff0000, v83
	v_lshlrev_b32_e32 v92, 16, v87
	v_and_b32_e32 v93, 0xffff0000, v87
	v_pk_mul_f32 v[94:95], v[40:41], v[94:95]
	s_nop 0
	v_pk_fma_f32 v[94:95], v[32:33], v[92:93], v[94:95]
	s_nop 0
	v_pk_fma_f32 v[94:95], v[48:49], v[96:97], v[94:95]
	s_nop 0
	v_pk_mul_f32 v[94:95], v[94:95], v[98:99]
	s_nop 0
	v_cvt_pk_bf16_f32 v79, v94, v95
	global_store_dwordx4 v100, v[76:79], s[14:15]
	s_waitcnt vmcnt(6)
	v_cmp_ne_u32_e32 vcc, 0, v127
	v_cmp_lt_u32_e64 s[0:1], 1, v127
	v_lshlrev_b32_e32 v122, 16, v102
	v_and_b32_e32 v123, 0xffff0000, v102
	v_lshlrev_b32_e32 v124, 16, v114
	v_and_b32_e32 v125, 0xffff0000, v114
	v_cndmask_b32_e32 v106, 0, v106, vcc
	v_cndmask_b32_e64 v110, 0, v110, s[0:1]
	v_lshlrev_b32_e32 v120, 16, v106
	v_and_b32_e32 v121, 0xffff0000, v106
	v_lshlrev_b32_e32 v118, 16, v110
	v_and_b32_e32 v119, 0xffff0000, v110
	v_pk_mul_f32 v[120:121], v[34:35], v[120:121]
	s_nop 0
	v_pk_fma_f32 v[120:121], v[26:27], v[118:119], v[120:121]
	s_nop 0
	v_pk_fma_f32 v[120:121], v[42:43], v[122:123], v[120:121]
	s_nop 0
	v_pk_mul_f32 v[120:121], v[120:121], v[124:125]
	s_nop 0
	v_cvt_pk_bf16_f32 v102, v120, v121
	v_lshlrev_b32_e32 v122, 16, v103
	v_and_b32_e32 v123, 0xffff0000, v103
	v_lshlrev_b32_e32 v124, 16, v115
	v_and_b32_e32 v125, 0xffff0000, v115
	v_cndmask_b32_e32 v107, 0, v107, vcc
	v_cndmask_b32_e64 v111, 0, v111, s[0:1]
	v_lshlrev_b32_e32 v120, 16, v107
	v_and_b32_e32 v121, 0xffff0000, v107
	v_lshlrev_b32_e32 v118, 16, v111
	v_and_b32_e32 v119, 0xffff0000, v111
	v_pk_mul_f32 v[120:121], v[36:37], v[120:121]
	s_nop 0
	v_pk_fma_f32 v[120:121], v[28:29], v[118:119], v[120:121]
	s_nop 0
	v_pk_fma_f32 v[120:121], v[44:45], v[122:123], v[120:121]
	s_nop 0
	v_pk_mul_f32 v[120:121], v[120:121], v[124:125]
	s_nop 0
	v_cvt_pk_bf16_f32 v103, v120, v121
	v_lshlrev_b32_e32 v122, 16, v104
	v_and_b32_e32 v123, 0xffff0000, v104
	v_lshlrev_b32_e32 v124, 16, v116
	v_and_b32_e32 v125, 0xffff0000, v116
	v_cndmask_b32_e32 v108, 0, v108, vcc
	v_cndmask_b32_e64 v112, 0, v112, s[0:1]
	v_lshlrev_b32_e32 v120, 16, v108
	v_and_b32_e32 v121, 0xffff0000, v108
	v_lshlrev_b32_e32 v118, 16, v112
	v_and_b32_e32 v119, 0xffff0000, v112
	v_pk_mul_f32 v[120:121], v[38:39], v[120:121]
	s_nop 0
	v_pk_fma_f32 v[120:121], v[30:31], v[118:119], v[120:121]
	s_nop 0
	v_pk_fma_f32 v[120:121], v[46:47], v[122:123], v[120:121]
	s_nop 0
	v_pk_mul_f32 v[120:121], v[120:121], v[124:125]
	s_nop 0
	v_cvt_pk_bf16_f32 v104, v120, v121
	v_lshlrev_b32_e32 v122, 16, v105
	v_and_b32_e32 v123, 0xffff0000, v105
	v_lshlrev_b32_e32 v124, 16, v117
	v_and_b32_e32 v125, 0xffff0000, v117
	v_cndmask_b32_e32 v109, 0, v109, vcc
	v_cndmask_b32_e64 v113, 0, v113, s[0:1]
	v_lshlrev_b32_e32 v120, 16, v109
	v_and_b32_e32 v121, 0xffff0000, v109
	v_lshlrev_b32_e32 v118, 16, v113
	v_and_b32_e32 v119, 0xffff0000, v113
	v_pk_mul_f32 v[120:121], v[40:41], v[120:121]
	s_nop 0
	v_pk_fma_f32 v[120:121], v[32:33], v[118:119], v[120:121]
	s_nop 0
	v_pk_fma_f32 v[120:121], v[48:49], v[122:123], v[120:121]
	s_nop 0
	v_pk_mul_f32 v[120:121], v[120:121], v[124:125]
	s_nop 0
	v_cvt_pk_bf16_f32 v105, v120, v121
	global_store_dwordx4 v126, v[102:105], s[14:15]
	s_waitcnt vmcnt(3)
; DI int tid() { int t = __builtin_amdgcn_workitem_id_x(); asm volatile("" : "+v"(t)); return t; }
; DI unsigned pk2(float a, float b) { f32x2 v = {a, b}; return __builtin_bit_cast(unsigned, __builtin_convertvector(v, bf2_t)); }
; DI float bf_lo(unsigned u) { return __uint_as_float(u << 16); }
; DI float bf_hi(unsigned u) { return __uint_as_float(u & 0xffff0000u); }
; DI void conv_pass(const Params& P, int layer) {
;     ...
;     for (int idx = blockIdx.x * 512 + tid(); idx < kT * 64; idx += gridDim.x * 512) {
;         const int tok = idx >> 6, c8 = (idx & 63) * 8, pos = tok & (kS - 1);
;         const u32x4 z4 = {0u, 0u, 0u, 0u};
;         const u32x4 c2 = *(const u32x4*)(cu + (size_t)tok * 512 + c8);
;         const u32x4 c1 = pos >= 1 ? *(const u32x4*)(cu + (size_t)(tok - 1) * 512 + c8) : z4;
;         const u32x4 c0 = pos >= 2 ? *(const u32x4*)(cu + (size_t)(tok - 2) * 512 + c8) : z4;
;         const u32x4 bv = *(const u32x4*)(bz + (size_t)tok * 512 + c8);
;         u32x4 o;
; #pragma unroll
;         for (int j = 0; j < 4; ++j) {
;             const int ch = c8 + 2 * j;
;             const float r0 = bf_lo(bv[j]) * (cw[ch] * bf_lo(c0[j]) + cw[512 + ch] * bf_lo(c1[j]) + cw[1024 + ch] * bf_lo(c2[j]));
;             const float r1 = bf_hi(bv[j]) * (cw[ch + 1] * bf_hi(c0[j]) + cw[512 + ch + 1] * bf_hi(c1[j]) + cw[1024 + ch + 1] * bf_hi(c2[j]));
;             o[j] = pk2(r0, r1);
;         }
;         *(u32x4*)(bz + (size_t)tok * 512 + c8) = o;
;     }
	v_cmp_ne_u32_e32 vcc, 0, v153
	v_cmp_lt_u32_e64 s[0:1], 1, v153
	v_lshlrev_b32_e32 v148, 16, v128
	v_and_b32_e32 v149, 0xffff0000, v128
	v_lshlrev_b32_e32 v150, 16, v140
	v_and_b32_e32 v151, 0xffff0000, v140
	v_cndmask_b32_e32 v132, 0, v132, vcc
	v_cndmask_b32_e64 v136, 0, v136, s[0:1]
	v_lshlrev_b32_e32 v146, 16, v132
	v_and_b32_e32 v147, 0xffff0000, v132
	v_lshlrev_b32_e32 v144, 16, v136
	v_and_b32_e32 v145, 0xffff0000, v136
	v_pk_mul_f32 v[146:147], v[34:35], v[146:147]
	s_nop 0
	v_pk_fma_f32 v[146:147], v[26:27], v[144:145], v[146:147]
	s_nop 0
	v_pk_fma_f32 v[146:147], v[42:43], v[148:149], v[146:147]
	s_nop 0
	v_pk_mul_f32 v[146:147], v[146:147], v[150:151]
	s_nop 0
	v_cvt_pk_bf16_f32 v128, v146, v147
	v_lshlrev_b32_e32 v148, 16, v129
	v_and_b32_e32 v149, 0xffff0000, v129
	v_lshlrev_b32_e32 v150, 16, v141
	v_and_b32_e32 v151, 0xffff0000, v141
	v_cndmask_b32_e32 v133, 0, v133, vcc
	v_cndmask_b32_e64 v137, 0, v137, s[0:1]
	v_lshlrev_b32_e32 v146, 16, v133
	v_and_b32_e32 v147, 0xffff0000, v133
	v_lshlrev_b32_e32 v144, 16, v137
	v_and_b32_e32 v145, 0xffff0000, v137
	v_pk_mul_f32 v[146:147], v[36:37], v[146:147]
	s_nop 0
	v_pk_fma_f32 v[146:147], v[28:29], v[144:145], v[146:147]
	s_nop 0
	v_pk_fma_f32 v[146:147], v[44:45], v[148:149], v[146:147]
	s_nop 0
	v_pk_mul_f32 v[146:147], v[146:147], v[150:151]
	s_nop 0
	v_cvt_pk_bf16_f32 v129, v146, v147
	v_lshlrev_b32_e32 v148, 16, v130
	v_and_b32_e32 v149, 0xffff0000, v130
	v_lshlrev_b32_e32 v150, 16, v142
	v_and_b32_e32 v151, 0xffff0000, v142
	v_cndmask_b32_e32 v134, 0, v134, vcc
	v_cndmask_b32_e64 v138, 0, v138, s[0:1]
	v_lshlrev_b32_e32 v146, 16, v134
	v_and_b32_e32 v147, 0xffff0000, v134
	v_lshlrev_b32_e32 v144, 16, v138
	v_and_b32_e32 v145, 0xffff0000, v138
	v_pk_mul_f32 v[146:147], v[38:39], v[146:147]
	s_nop 0
	v_pk_fma_f32 v[146:147], v[30:31], v[144:145], v[146:147]
	s_nop 0
	v_pk_fma_f32 v[146:147], v[46:47], v[148:149], v[146:147]
	s_nop 0
	v_pk_mul_f32 v[146:147], v[146:147], v[150:151]
	s_nop 0
	v_cvt_pk_bf16_f32 v130, v146, v147
	v_lshlrev_b32_e32 v148, 16, v131
	v_and_b32_e32 v149, 0xffff0000, v131
	v_lshlrev_b32_e32 v150, 16, v143
	v_and_b32_e32 v151, 0xffff0000, v143
	v_cndmask_b32_e32 v135, 0, v135, vcc
	v_cndmask_b32_e64 v139, 0, v139, s[0:1]
	v_lshlrev_b32_e32 v146, 16, v135
	v_and_b32_e32 v147, 0xffff0000, v135
	v_lshlrev_b32_e32 v144, 16, v139
	v_and_b32_e32 v145, 0xffff0000, v139
	v_pk_mul_f32 v[146:147], v[40:41], v[146:147]
	s_nop 0
	v_pk_fma_f32 v[146:147], v[32:33], v[144:145], v[146:147]
	s_nop 0
	v_pk_fma_f32 v[146:147], v[48:49], v[148:149], v[146:147]
	s_nop 0
	v_pk_mul_f32 v[146:147], v[146:147], v[150:151]
	s_nop 0
	v_cvt_pk_bf16_f32 v131, v146, v147
	global_store_dwordx4 v152, v[128:131], s[14:15]
	s_lshl_b32 s0, s2, 2
	s_lshl_b32 s1, s3, 2
	v_add_u32_e32 v24, s0, v24
	v_add_u32_e32 v25, s1, v25
	s_mul_i32 s0, s2, 3
	s_mov_b32 s1, 0x200000
	v_add_u32_e32 v5, s0, v24
	v_cmp_gt_i32_e32 vcc, s1, v5
	s_cbranch_vccnz .Lconv_loop
	v_cmp_gt_i32_e32 vcc, s1, v24
	s_and_b64 exec, exec, vcc
	s_cbranch_execz .LBB0_78
	s_branch .LBB0_73
